# prompt RWKV scan inner loop rewritten by hand: 32 steps per chunk iteration, y row-sums via deferred 16-step DPP reduce-scatter instead of per-step all-reduce+select, LDS loads prefetched 2 steps ahea
# speedup vs baseline: 1.0212x; 1.0212x over previous
.LBB0_994:
	s_and_b64 vcc, exec, s[0:1]
	s_cbranch_vccz .LBB0_1002
	s_lshl_b32 s4, s26, 4
	s_lshl_b32 s5, s27, 2
	s_or_b32 s0, s5, s4
	s_waitcnt vmcnt(0)
	v_lshrrev_b32_e32 v2, 4, v100
	v_or_b32_e32 v100, s0, v2
	s_lshl_b32 s0, s24, 24
	s_add_u32 s0, s94, s0
	s_addc_u32 s1, s95, 0
	s_lshl_b32 s6, s25, 7
	s_add_u32 s0, s0, s6
	s_addc_u32 s1, s1, 0
	v_mov_b32_e32 v103, 0
	v_lshlrev_b32_e32 v102, 1, v100
	v_lshl_add_u64 v[0:1], s[0:1], 0, v[102:103]
	s_mov_b64 s[0:1], 0x6a00000
	s_add_i32 s5, s5, s4
	v_lshl_add_u64 v[104:105], v[0:1], 0, s[0:1]
	v_or_b32_e32 v0, s5, v2
	v_and_b32_e32 v110, 15, v166
	v_lshl_add_u32 v0, v0, 2, 0
	v_mov_b32_e32 v102, v103
	v_mov_b32_e32 v101, v103
	v_lshlrev_b32_e32 v111, 11, v110
	v_add_u32_e32 v112, 0x500, v0
	v_lshl_add_u32 v113, v110, 4, 0
	s_mov_b32 s6, 0
	s_movk_i32 s7, 0x7fff
	v_mov_b64_e32 v[0:1], v[102:103]
	v_mov_b64_e32 v[2:3], v[102:103]
	s_mov_b32 s4, 0x22222222
	s_mov_b32 s5, 0x22222222
	s_mov_b32 s10, 0x44444444
	s_mov_b32 s11, 0x44444444
	s_mov_b32 s12, 0x88888888
	s_mov_b32 s13, 0x88888888
	s_barrier
.LBB0_996:
	s_bitcmp1_b32 s6, 0
	s_cselect_b32 s0, 0xc000, 0
	v_lshl_or_b32 v114, s6, 16, v111
	v_add_u32_e32 v115, s0, v112
	v_add_u32_e32 v116, s0, v113
	ds_read_b128 v[8:11], v116 offset:256
	ds_read2st64_b32 v[64:65], v115 offset1:6
	ds_read_b128 v[12:15], v116 offset:512
	ds_read_b128 v[4:7], v116
	ds_read_b128 v[16:19], v116 offset:768
	ds_read_b128 v[20:23], v116 offset:1024
	ds_read_b128 v[28:31], v116 offset:1792
	ds_read_b128 v[32:35], v116 offset:2048
	ds_read_b128 v[24:27], v116 offset:1536
	ds_read_b128 v[36:39], v116 offset:2304
	ds_read_b128 v[40:43], v116 offset:2560
	s_waitcnt lgkmcnt(5)
	v_pk_mul_f32 v[86:87], v[2:3], v[14:15]
	v_pk_fma_f32 v[86:87], v[0:1], v[12:13], v[86:87]
	v_add_f32_e32 v98, v86, v87
	v_pk_mul_f32 v[88:89], v[8:9], v[64:65] op_sel_hi:[1,0]
	v_pk_mul_f32 v[90:91], v[10:11], v[64:65] op_sel_hi:[1,0]
	v_add_f32_dpp v98, v98, v98 quad_perm:[1,0,3,2] row_mask:0xf bank_mask:0xf bound_ctrl:1
	v_pk_fma_f32 v[92:93], v[0:1], v[4:5], v[88:89]
	v_pk_fma_f32 v[94:95], v[2:3], v[6:7], v[90:91]
	v_add_f32_dpp v98, v98, v98 quad_perm:[2,3,0,1] row_mask:0xf bank_mask:0xf bound_ctrl:1
	ds_read_b128 v[48:51], v116 offset:3328
	ds_read2st64_b32 v[66:67], v115 offset0:12 offset1:18
	v_add_f32_dpp v98, v98, v98 row_half_mirror row_mask:0xf bank_mask:0xf bound_ctrl:1
	ds_read_b128 v[52:55], v116 offset:3584
	ds_read_b128 v[44:47], v116 offset:3072
	v_add_f32_dpp v98, v98, v98 row_mirror row_mask:0xf bank_mask:0xf bound_ctrl:1
	v_pk_fma_f32 v[0:1], v[16:17], v[98:99], v[92:93] op_sel_hi:[1,0,1]
	v_pk_fma_f32 v[2:3], v[18:19], v[98:99], v[94:95] op_sel_hi:[1,0,1]
	ds_read_b128 v[56:59], v116 offset:3840
	ds_read_b128 v[60:63], v116 offset:4096
	s_waitcnt lgkmcnt(6)
	v_pk_mul_f32 v[86:87], v[2:3], v[34:35]
	v_pk_mul_f32 v[96:97], v[22:23], v[2:3]
	v_pk_fma_f32 v[86:87], v[0:1], v[32:33], v[86:87]
	v_pk_fma_f32 v[96:97], v[20:21], v[0:1], v[96:97]
	v_add_f32_e32 v98, v86, v87
	v_pk_mul_f32 v[88:89], v[28:29], v[64:65] op_sel:[0,1] op_sel_hi:[1,1]
	v_pk_mul_f32 v[90:91], v[30:31], v[64:65] op_sel:[0,1] op_sel_hi:[1,1]
	v_add_f32_dpp v98, v98, v98 quad_perm:[1,0,3,2] row_mask:0xf bank_mask:0xf bound_ctrl:1
	v_pk_fma_f32 v[92:93], v[0:1], v[24:25], v[88:89]
	v_pk_fma_f32 v[94:95], v[2:3], v[26:27], v[90:91]
	v_add_f32_dpp v98, v98, v98 quad_perm:[2,3,0,1] row_mask:0xf bank_mask:0xf bound_ctrl:1
	v_add_f32_e32 v70, v96, v97
	ds_read_b128 v[8:11], v116 offset:4864
	v_add_f32_dpp v98, v98, v98 row_half_mirror row_mask:0xf bank_mask:0xf bound_ctrl:1
	ds_read_b128 v[12:15], v116 offset:5120
	ds_read_b128 v[4:7], v116 offset:4608
	v_add_f32_dpp v98, v98, v98 row_mirror row_mask:0xf bank_mask:0xf bound_ctrl:1
	v_pk_fma_f32 v[0:1], v[36:37], v[98:99], v[92:93] op_sel_hi:[1,0,1]
	v_pk_fma_f32 v[2:3], v[38:39], v[98:99], v[94:95] op_sel_hi:[1,0,1]
	ds_read_b128 v[16:19], v116 offset:5376
	ds_read_b128 v[20:23], v116 offset:5632
	s_waitcnt lgkmcnt(5)
	v_pk_mul_f32 v[86:87], v[2:3], v[54:55]
	v_pk_mul_f32 v[96:97], v[42:43], v[2:3]
	v_pk_fma_f32 v[86:87], v[0:1], v[52:53], v[86:87]
	v_pk_fma_f32 v[96:97], v[40:41], v[0:1], v[96:97]
	v_add_f32_e32 v98, v86, v87
	v_pk_mul_f32 v[88:89], v[48:49], v[66:67] op_sel_hi:[1,0]
	v_pk_mul_f32 v[90:91], v[50:51], v[66:67] op_sel_hi:[1,0]
	v_add_f32_dpp v98, v98, v98 quad_perm:[1,0,3,2] row_mask:0xf bank_mask:0xf bound_ctrl:1
	v_pk_fma_f32 v[92:93], v[0:1], v[44:45], v[88:89]
	v_pk_fma_f32 v[94:95], v[2:3], v[46:47], v[90:91]
	v_add_f32_dpp v98, v98, v98 quad_perm:[2,3,0,1] row_mask:0xf bank_mask:0xf bound_ctrl:1
	v_add_f32_e32 v71, v96, v97
	ds_read_b128 v[28:31], v116 offset:6400
	v_add_f32_dpp v98, v98, v98 row_half_mirror row_mask:0xf bank_mask:0xf bound_ctrl:1
	ds_read2st64_b32 v[64:65], v115 offset0:24 offset1:30
	ds_read_b128 v[32:35], v116 offset:6656
	v_add_f32_dpp v98, v98, v98 row_mirror row_mask:0xf bank_mask:0xf bound_ctrl:1
	v_pk_fma_f32 v[0:1], v[56:57], v[98:99], v[92:93] op_sel_hi:[1,0,1]
	v_pk_fma_f32 v[2:3], v[58:59], v[98:99], v[94:95] op_sel_hi:[1,0,1]
	ds_read_b128 v[24:27], v116 offset:6144
	ds_read_b128 v[36:39], v116 offset:6912
	ds_read_b128 v[40:43], v116 offset:7168
	s_waitcnt lgkmcnt(6)
	v_pk_mul_f32 v[86:87], v[2:3], v[14:15]
	v_pk_mul_f32 v[96:97], v[62:63], v[2:3]
	v_pk_fma_f32 v[86:87], v[0:1], v[12:13], v[86:87]
	v_pk_fma_f32 v[96:97], v[60:61], v[0:1], v[96:97]
	v_add_f32_e32 v98, v86, v87
	v_pk_mul_f32 v[88:89], v[8:9], v[66:67] op_sel:[0,1] op_sel_hi:[1,1]
	v_pk_mul_f32 v[90:91], v[10:11], v[66:67] op_sel:[0,1] op_sel_hi:[1,1]
	v_add_f32_dpp v98, v98, v98 quad_perm:[1,0,3,2] row_mask:0xf bank_mask:0xf bound_ctrl:1
	v_pk_fma_f32 v[92:93], v[0:1], v[4:5], v[88:89]
	v_pk_fma_f32 v[94:95], v[2:3], v[6:7], v[90:91]
	v_add_f32_dpp v98, v98, v98 quad_perm:[2,3,0,1] row_mask:0xf bank_mask:0xf bound_ctrl:1
	v_add_f32_e32 v72, v96, v97
	ds_read_b128 v[48:51], v116 offset:7936
	v_add_f32_dpp v98, v98, v98 row_half_mirror row_mask:0xf bank_mask:0xf bound_ctrl:1
	ds_read_b128 v[52:55], v116 offset:8192
	ds_read_b128 v[44:47], v116 offset:7680
	v_add_f32_dpp v98, v98, v98 row_mirror row_mask:0xf bank_mask:0xf bound_ctrl:1
	v_pk_fma_f32 v[0:1], v[16:17], v[98:99], v[92:93] op_sel_hi:[1,0,1]
	v_pk_fma_f32 v[2:3], v[18:19], v[98:99], v[94:95] op_sel_hi:[1,0,1]
	ds_read_b128 v[56:59], v116 offset:8448
	ds_read_b128 v[60:63], v116 offset:8704
	s_waitcnt lgkmcnt(5)
	v_pk_mul_f32 v[86:87], v[2:3], v[34:35]
	v_pk_mul_f32 v[96:97], v[22:23], v[2:3]
	v_pk_fma_f32 v[86:87], v[0:1], v[32:33], v[86:87]
	v_pk_fma_f32 v[96:97], v[20:21], v[0:1], v[96:97]
	v_add_f32_e32 v98, v86, v87
	v_pk_mul_f32 v[88:89], v[28:29], v[64:65] op_sel_hi:[1,0]
	v_pk_mul_f32 v[90:91], v[30:31], v[64:65] op_sel_hi:[1,0]
	v_add_f32_dpp v98, v98, v98 quad_perm:[1,0,3,2] row_mask:0xf bank_mask:0xf bound_ctrl:1
	v_pk_fma_f32 v[92:93], v[0:1], v[24:25], v[88:89]
	v_pk_fma_f32 v[94:95], v[2:3], v[26:27], v[90:91]
	v_add_f32_dpp v98, v98, v98 quad_perm:[2,3,0,1] row_mask:0xf bank_mask:0xf bound_ctrl:1
	v_add_f32_e32 v73, v96, v97
	ds_read_b128 v[8:11], v116 offset:9472
	v_add_f32_dpp v98, v98, v98 row_half_mirror row_mask:0xf bank_mask:0xf bound_ctrl:1
	ds_read2st64_b32 v[66:67], v115 offset0:36 offset1:42
	ds_read_b128 v[12:15], v116 offset:9728
	v_add_f32_dpp v98, v98, v98 row_mirror row_mask:0xf bank_mask:0xf bound_ctrl:1
	v_pk_fma_f32 v[0:1], v[36:37], v[98:99], v[92:93] op_sel_hi:[1,0,1]
	v_pk_fma_f32 v[2:3], v[38:39], v[98:99], v[94:95] op_sel_hi:[1,0,1]
	ds_read_b128 v[4:7], v116 offset:9216
	ds_read_b128 v[16:19], v116 offset:9984
	ds_read_b128 v[20:23], v116 offset:10240
	s_waitcnt lgkmcnt(6)
	v_pk_mul_f32 v[86:87], v[2:3], v[54:55]
	v_pk_mul_f32 v[96:97], v[42:43], v[2:3]
	v_pk_fma_f32 v[86:87], v[0:1], v[52:53], v[86:87]
	v_pk_fma_f32 v[96:97], v[40:41], v[0:1], v[96:97]
	v_add_f32_e32 v98, v86, v87
	v_pk_mul_f32 v[88:89], v[48:49], v[64:65] op_sel:[0,1] op_sel_hi:[1,1]
	v_pk_mul_f32 v[90:91], v[50:51], v[64:65] op_sel:[0,1] op_sel_hi:[1,1]
	v_add_f32_dpp v98, v98, v98 quad_perm:[1,0,3,2] row_mask:0xf bank_mask:0xf bound_ctrl:1
	v_pk_fma_f32 v[92:93], v[0:1], v[44:45], v[88:89]
	v_pk_fma_f32 v[94:95], v[2:3], v[46:47], v[90:91]
	v_add_f32_dpp v98, v98, v98 quad_perm:[2,3,0,1] row_mask:0xf bank_mask:0xf bound_ctrl:1
	v_add_f32_e32 v74, v96, v97
	ds_read_b128 v[28:31], v116 offset:11008
	v_add_f32_dpp v98, v98, v98 row_half_mirror row_mask:0xf bank_mask:0xf bound_ctrl:1
	ds_read_b128 v[32:35], v116 offset:11264
	ds_read_b128 v[24:27], v116 offset:10752
	v_add_f32_dpp v98, v98, v98 row_mirror row_mask:0xf bank_mask:0xf bound_ctrl:1
	v_pk_fma_f32 v[0:1], v[56:57], v[98:99], v[92:93] op_sel_hi:[1,0,1]
	v_pk_fma_f32 v[2:3], v[58:59], v[98:99], v[94:95] op_sel_hi:[1,0,1]
	ds_read_b128 v[36:39], v116 offset:11520
	ds_read_b128 v[40:43], v116 offset:11776
	s_waitcnt lgkmcnt(5)
	v_pk_mul_f32 v[86:87], v[2:3], v[14:15]
	v_pk_mul_f32 v[96:97], v[62:63], v[2:3]
	v_pk_fma_f32 v[86:87], v[0:1], v[12:13], v[86:87]
	v_pk_fma_f32 v[96:97], v[60:61], v[0:1], v[96:97]
	v_add_f32_e32 v98, v86, v87
	v_pk_mul_f32 v[88:89], v[8:9], v[66:67] op_sel_hi:[1,0]
	v_pk_mul_f32 v[90:91], v[10:11], v[66:67] op_sel_hi:[1,0]
	v_add_f32_dpp v98, v98, v98 quad_perm:[1,0,3,2] row_mask:0xf bank_mask:0xf bound_ctrl:1
	v_pk_fma_f32 v[92:93], v[0:1], v[4:5], v[88:89]
	v_pk_fma_f32 v[94:95], v[2:3], v[6:7], v[90:91]
	v_add_f32_dpp v98, v98, v98 quad_perm:[2,3,0,1] row_mask:0xf bank_mask:0xf bound_ctrl:1
	v_add_f32_e32 v75, v96, v97
	ds_read_b128 v[48:51], v116 offset:12544
	v_add_f32_dpp v98, v98, v98 row_half_mirror row_mask:0xf bank_mask:0xf bound_ctrl:1
	ds_read2st64_b32 v[64:65], v115 offset0:48 offset1:54
	ds_read_b128 v[52:55], v116 offset:12800
	v_add_f32_dpp v98, v98, v98 row_mirror row_mask:0xf bank_mask:0xf bound_ctrl:1
	v_pk_fma_f32 v[0:1], v[16:17], v[98:99], v[92:93] op_sel_hi:[1,0,1]
	v_pk_fma_f32 v[2:3], v[18:19], v[98:99], v[94:95] op_sel_hi:[1,0,1]
	ds_read_b128 v[44:47], v116 offset:12288
	ds_read_b128 v[56:59], v116 offset:13056
	ds_read_b128 v[60:63], v116 offset:13312
	s_waitcnt lgkmcnt(6)
	v_pk_mul_f32 v[86:87], v[2:3], v[34:35]
	v_pk_mul_f32 v[96:97], v[22:23], v[2:3]
	v_pk_fma_f32 v[86:87], v[0:1], v[32:33], v[86:87]
	v_pk_fma_f32 v[96:97], v[20:21], v[0:1], v[96:97]
	v_add_f32_e32 v98, v86, v87
	v_pk_mul_f32 v[88:89], v[28:29], v[66:67] op_sel:[0,1] op_sel_hi:[1,1]
	v_pk_mul_f32 v[90:91], v[30:31], v[66:67] op_sel:[0,1] op_sel_hi:[1,1]
	v_add_f32_dpp v98, v98, v98 quad_perm:[1,0,3,2] row_mask:0xf bank_mask:0xf bound_ctrl:1
	v_pk_fma_f32 v[92:93], v[0:1], v[24:25], v[88:89]
	v_pk_fma_f32 v[94:95], v[2:3], v[26:27], v[90:91]
	v_add_f32_dpp v98, v98, v98 quad_perm:[2,3,0,1] row_mask:0xf bank_mask:0xf bound_ctrl:1
	v_add_f32_e32 v76, v96, v97
	ds_read_b128 v[8:11], v116 offset:14080
	v_add_f32_dpp v98, v98, v98 row_half_mirror row_mask:0xf bank_mask:0xf bound_ctrl:1
	ds_read_b128 v[12:15], v116 offset:14336
	ds_read_b128 v[4:7], v116 offset:13824
	v_add_f32_dpp v98, v98, v98 row_mirror row_mask:0xf bank_mask:0xf bound_ctrl:1
	v_pk_fma_f32 v[0:1], v[36:37], v[98:99], v[92:93] op_sel_hi:[1,0,1]
	v_pk_fma_f32 v[2:3], v[38:39], v[98:99], v[94:95] op_sel_hi:[1,0,1]
	ds_read_b128 v[16:19], v116 offset:14592
	ds_read_b128 v[20:23], v116 offset:14848
	s_waitcnt lgkmcnt(5)
	v_pk_mul_f32 v[86:87], v[2:3], v[54:55]
	v_pk_mul_f32 v[96:97], v[42:43], v[2:3]
	v_pk_fma_f32 v[86:87], v[0:1], v[52:53], v[86:87]
	v_pk_fma_f32 v[96:97], v[40:41], v[0:1], v[96:97]
	v_add_f32_e32 v98, v86, v87
	v_pk_mul_f32 v[88:89], v[48:49], v[64:65] op_sel_hi:[1,0]
	v_pk_mul_f32 v[90:91], v[50:51], v[64:65] op_sel_hi:[1,0]
	v_add_f32_dpp v98, v98, v98 quad_perm:[1,0,3,2] row_mask:0xf bank_mask:0xf bound_ctrl:1
	v_pk_fma_f32 v[92:93], v[0:1], v[44:45], v[88:89]
	v_pk_fma_f32 v[94:95], v[2:3], v[46:47], v[90:91]
	v_add_f32_dpp v98, v98, v98 quad_perm:[2,3,0,1] row_mask:0xf bank_mask:0xf bound_ctrl:1
	v_add_f32_e32 v77, v96, v97
	ds_read_b128 v[28:31], v116 offset:15616
	v_add_f32_dpp v98, v98, v98 row_half_mirror row_mask:0xf bank_mask:0xf bound_ctrl:1
	ds_read2st64_b32 v[66:67], v115 offset0:60 offset1:66
	ds_read_b128 v[32:35], v116 offset:15872
	v_add_f32_dpp v98, v98, v98 row_mirror row_mask:0xf bank_mask:0xf bound_ctrl:1
	v_pk_fma_f32 v[0:1], v[56:57], v[98:99], v[92:93] op_sel_hi:[1,0,1]
	v_pk_fma_f32 v[2:3], v[58:59], v[98:99], v[94:95] op_sel_hi:[1,0,1]
	ds_read_b128 v[24:27], v116 offset:15360
	ds_read_b128 v[36:39], v116 offset:16128
	ds_read_b128 v[40:43], v116 offset:16384
	s_waitcnt lgkmcnt(6)
	v_pk_mul_f32 v[86:87], v[2:3], v[14:15]
	v_pk_mul_f32 v[96:97], v[62:63], v[2:3]
	v_pk_fma_f32 v[86:87], v[0:1], v[12:13], v[86:87]
	v_pk_fma_f32 v[96:97], v[60:61], v[0:1], v[96:97]
	v_add_f32_e32 v98, v86, v87
	v_pk_mul_f32 v[88:89], v[8:9], v[64:65] op_sel:[0,1] op_sel_hi:[1,1]
	v_pk_mul_f32 v[90:91], v[10:11], v[64:65] op_sel:[0,1] op_sel_hi:[1,1]
	v_add_f32_dpp v98, v98, v98 quad_perm:[1,0,3,2] row_mask:0xf bank_mask:0xf bound_ctrl:1
	v_pk_fma_f32 v[92:93], v[0:1], v[4:5], v[88:89]
	v_pk_fma_f32 v[94:95], v[2:3], v[6:7], v[90:91]
	v_add_f32_dpp v98, v98, v98 quad_perm:[2,3,0,1] row_mask:0xf bank_mask:0xf bound_ctrl:1
	v_add_f32_e32 v78, v96, v97
	ds_read_b128 v[48:51], v116 offset:17152
	v_add_f32_dpp v98, v98, v98 row_half_mirror row_mask:0xf bank_mask:0xf bound_ctrl:1
	ds_read_b128 v[52:55], v116 offset:17408
	ds_read_b128 v[44:47], v116 offset:16896
	v_add_f32_dpp v98, v98, v98 row_mirror row_mask:0xf bank_mask:0xf bound_ctrl:1
	v_pk_fma_f32 v[0:1], v[16:17], v[98:99], v[92:93] op_sel_hi:[1,0,1]
	v_pk_fma_f32 v[2:3], v[18:19], v[98:99], v[94:95] op_sel_hi:[1,0,1]
	ds_read_b128 v[56:59], v116 offset:17664
	ds_read_b128 v[60:63], v116 offset:17920
	s_waitcnt lgkmcnt(5)
	v_pk_mul_f32 v[86:87], v[2:3], v[34:35]
	v_pk_mul_f32 v[96:97], v[22:23], v[2:3]
	v_pk_fma_f32 v[86:87], v[0:1], v[32:33], v[86:87]
	v_pk_fma_f32 v[96:97], v[20:21], v[0:1], v[96:97]
	v_add_f32_e32 v98, v86, v87
	v_pk_mul_f32 v[88:89], v[28:29], v[66:67] op_sel_hi:[1,0]
	v_pk_mul_f32 v[90:91], v[30:31], v[66:67] op_sel_hi:[1,0]
	v_add_f32_dpp v98, v98, v98 quad_perm:[1,0,3,2] row_mask:0xf bank_mask:0xf bound_ctrl:1
	v_pk_fma_f32 v[92:93], v[0:1], v[24:25], v[88:89]
	v_pk_fma_f32 v[94:95], v[2:3], v[26:27], v[90:91]
	v_add_f32_dpp v98, v98, v98 quad_perm:[2,3,0,1] row_mask:0xf bank_mask:0xf bound_ctrl:1
	v_add_f32_e32 v79, v96, v97
	ds_read_b128 v[8:11], v116 offset:18688
	v_add_f32_dpp v98, v98, v98 row_half_mirror row_mask:0xf bank_mask:0xf bound_ctrl:1
	ds_read2st64_b32 v[64:65], v115 offset0:72 offset1:78
	ds_read_b128 v[12:15], v116 offset:18944
	v_add_f32_dpp v98, v98, v98 row_mirror row_mask:0xf bank_mask:0xf bound_ctrl:1
	v_pk_fma_f32 v[0:1], v[36:37], v[98:99], v[92:93] op_sel_hi:[1,0,1]
	v_pk_fma_f32 v[2:3], v[38:39], v[98:99], v[94:95] op_sel_hi:[1,0,1]
	ds_read_b128 v[4:7], v116 offset:18432
	ds_read_b128 v[16:19], v116 offset:19200
	ds_read_b128 v[20:23], v116 offset:19456
	s_waitcnt lgkmcnt(6)
	v_pk_mul_f32 v[86:87], v[2:3], v[54:55]
	v_pk_mul_f32 v[96:97], v[42:43], v[2:3]
	v_pk_fma_f32 v[86:87], v[0:1], v[52:53], v[86:87]
	v_pk_fma_f32 v[96:97], v[40:41], v[0:1], v[96:97]
	v_add_f32_e32 v98, v86, v87
	v_pk_mul_f32 v[88:89], v[48:49], v[66:67] op_sel:[0,1] op_sel_hi:[1,1]
	v_pk_mul_f32 v[90:91], v[50:51], v[66:67] op_sel:[0,1] op_sel_hi:[1,1]
	v_add_f32_dpp v98, v98, v98 quad_perm:[1,0,3,2] row_mask:0xf bank_mask:0xf bound_ctrl:1
	v_pk_fma_f32 v[92:93], v[0:1], v[44:45], v[88:89]
	v_pk_fma_f32 v[94:95], v[2:3], v[46:47], v[90:91]
	v_add_f32_dpp v98, v98, v98 quad_perm:[2,3,0,1] row_mask:0xf bank_mask:0xf bound_ctrl:1
	v_add_f32_e32 v80, v96, v97
	ds_read_b128 v[28:31], v116 offset:20224
	v_add_f32_dpp v98, v98, v98 row_half_mirror row_mask:0xf bank_mask:0xf bound_ctrl:1
	ds_read_b128 v[32:35], v116 offset:20480
	ds_read_b128 v[24:27], v116 offset:19968
	v_add_f32_dpp v98, v98, v98 row_mirror row_mask:0xf bank_mask:0xf bound_ctrl:1
	v_pk_fma_f32 v[0:1], v[56:57], v[98:99], v[92:93] op_sel_hi:[1,0,1]
	v_pk_fma_f32 v[2:3], v[58:59], v[98:99], v[94:95] op_sel_hi:[1,0,1]
	ds_read_b128 v[36:39], v116 offset:20736
	ds_read_b128 v[40:43], v116 offset:20992
	s_waitcnt lgkmcnt(5)
	v_pk_mul_f32 v[86:87], v[2:3], v[14:15]
	v_pk_mul_f32 v[96:97], v[62:63], v[2:3]
	v_pk_fma_f32 v[86:87], v[0:1], v[12:13], v[86:87]
	v_pk_fma_f32 v[96:97], v[60:61], v[0:1], v[96:97]
	v_add_f32_e32 v98, v86, v87
	v_pk_mul_f32 v[88:89], v[8:9], v[64:65] op_sel_hi:[1,0]
	v_pk_mul_f32 v[90:91], v[10:11], v[64:65] op_sel_hi:[1,0]
	v_add_f32_dpp v98, v98, v98 quad_perm:[1,0,3,2] row_mask:0xf bank_mask:0xf bound_ctrl:1
	v_pk_fma_f32 v[92:93], v[0:1], v[4:5], v[88:89]
	v_pk_fma_f32 v[94:95], v[2:3], v[6:7], v[90:91]
	v_add_f32_dpp v98, v98, v98 quad_perm:[2,3,0,1] row_mask:0xf bank_mask:0xf bound_ctrl:1
	v_add_f32_e32 v81, v96, v97
	ds_read_b128 v[48:51], v116 offset:21760
	v_add_f32_dpp v98, v98, v98 row_half_mirror row_mask:0xf bank_mask:0xf bound_ctrl:1
	ds_read2st64_b32 v[66:67], v115 offset0:84 offset1:90
	ds_read_b128 v[52:55], v116 offset:22016
	v_add_f32_dpp v98, v98, v98 row_mirror row_mask:0xf bank_mask:0xf bound_ctrl:1
	v_pk_fma_f32 v[0:1], v[16:17], v[98:99], v[92:93] op_sel_hi:[1,0,1]
	v_pk_fma_f32 v[2:3], v[18:19], v[98:99], v[94:95] op_sel_hi:[1,0,1]
	ds_read_b128 v[44:47], v116 offset:21504
	ds_read_b128 v[56:59], v116 offset:22272
	ds_read_b128 v[60:63], v116 offset:22528
	s_waitcnt lgkmcnt(6)
	v_pk_mul_f32 v[86:87], v[2:3], v[34:35]
	v_pk_mul_f32 v[96:97], v[22:23], v[2:3]
	v_pk_fma_f32 v[86:87], v[0:1], v[32:33], v[86:87]
	v_pk_fma_f32 v[96:97], v[20:21], v[0:1], v[96:97]
	v_add_f32_e32 v98, v86, v87
	v_pk_mul_f32 v[88:89], v[28:29], v[64:65] op_sel:[0,1] op_sel_hi:[1,1]
	v_pk_mul_f32 v[90:91], v[30:31], v[64:65] op_sel:[0,1] op_sel_hi:[1,1]
	v_add_f32_dpp v98, v98, v98 quad_perm:[1,0,3,2] row_mask:0xf bank_mask:0xf bound_ctrl:1
	v_pk_fma_f32 v[92:93], v[0:1], v[24:25], v[88:89]
	v_pk_fma_f32 v[94:95], v[2:3], v[26:27], v[90:91]
	v_add_f32_dpp v98, v98, v98 quad_perm:[2,3,0,1] row_mask:0xf bank_mask:0xf bound_ctrl:1
	v_add_f32_e32 v82, v96, v97
	ds_read_b128 v[8:11], v116 offset:23296
	v_add_f32_dpp v98, v98, v98 row_half_mirror row_mask:0xf bank_mask:0xf bound_ctrl:1
	ds_read_b128 v[12:15], v116 offset:23552
	ds_read_b128 v[4:7], v116 offset:23040
	v_add_f32_dpp v98, v98, v98 row_mirror row_mask:0xf bank_mask:0xf bound_ctrl:1
	v_pk_fma_f32 v[0:1], v[36:37], v[98:99], v[92:93] op_sel_hi:[1,0,1]
	v_pk_fma_f32 v[2:3], v[38:39], v[98:99], v[94:95] op_sel_hi:[1,0,1]
	ds_read_b128 v[16:19], v116 offset:23808
	ds_read_b128 v[20:23], v116 offset:24064
	s_waitcnt lgkmcnt(5)
	v_pk_mul_f32 v[86:87], v[2:3], v[54:55]
	v_pk_mul_f32 v[96:97], v[42:43], v[2:3]
	v_pk_fma_f32 v[86:87], v[0:1], v[52:53], v[86:87]
	v_pk_fma_f32 v[96:97], v[40:41], v[0:1], v[96:97]
	v_add_f32_e32 v98, v86, v87
	v_pk_mul_f32 v[88:89], v[48:49], v[66:67] op_sel_hi:[1,0]
	v_pk_mul_f32 v[90:91], v[50:51], v[66:67] op_sel_hi:[1,0]
	v_add_f32_dpp v98, v98, v98 quad_perm:[1,0,3,2] row_mask:0xf bank_mask:0xf bound_ctrl:1
	v_pk_fma_f32 v[92:93], v[0:1], v[44:45], v[88:89]
	v_pk_fma_f32 v[94:95], v[2:3], v[46:47], v[90:91]
	v_add_f32_dpp v98, v98, v98 quad_perm:[2,3,0,1] row_mask:0xf bank_mask:0xf bound_ctrl:1
	v_add_f32_e32 v83, v96, v97
	ds_read_b128 v[28:31], v116 offset:24832
	v_add_f32_dpp v98, v98, v98 row_half_mirror row_mask:0xf bank_mask:0xf bound_ctrl:1
	ds_read2st64_b32 v[64:65], v115 offset0:96 offset1:102
	ds_read_b128 v[32:35], v116 offset:25088
	v_add_f32_dpp v98, v98, v98 row_mirror row_mask:0xf bank_mask:0xf bound_ctrl:1
	v_pk_fma_f32 v[0:1], v[56:57], v[98:99], v[92:93] op_sel_hi:[1,0,1]
	v_pk_fma_f32 v[2:3], v[58:59], v[98:99], v[94:95] op_sel_hi:[1,0,1]
	ds_read_b128 v[24:27], v116 offset:24576
	ds_read_b128 v[36:39], v116 offset:25344
	ds_read_b128 v[40:43], v116 offset:25600
	s_waitcnt lgkmcnt(6)
	v_pk_mul_f32 v[86:87], v[2:3], v[14:15]
	v_pk_mul_f32 v[96:97], v[62:63], v[2:3]
	v_pk_fma_f32 v[86:87], v[0:1], v[12:13], v[86:87]
	v_pk_fma_f32 v[96:97], v[60:61], v[0:1], v[96:97]
	v_add_f32_e32 v98, v86, v87
	v_pk_mul_f32 v[88:89], v[8:9], v[66:67] op_sel:[0,1] op_sel_hi:[1,1]
	v_pk_mul_f32 v[90:91], v[10:11], v[66:67] op_sel:[0,1] op_sel_hi:[1,1]
	v_add_f32_dpp v98, v98, v98 quad_perm:[1,0,3,2] row_mask:0xf bank_mask:0xf bound_ctrl:1
	v_pk_fma_f32 v[92:93], v[0:1], v[4:5], v[88:89]
	v_pk_fma_f32 v[94:95], v[2:3], v[6:7], v[90:91]
	v_add_f32_dpp v98, v98, v98 quad_perm:[2,3,0,1] row_mask:0xf bank_mask:0xf bound_ctrl:1
	v_add_f32_e32 v84, v96, v97
	ds_read_b128 v[48:51], v116 offset:26368
	v_add_f32_dpp v98, v98, v98 row_half_mirror row_mask:0xf bank_mask:0xf bound_ctrl:1
	ds_read_b128 v[52:55], v116 offset:26624
	ds_read_b128 v[44:47], v116 offset:26112
	v_add_f32_dpp v98, v98, v98 row_mirror row_mask:0xf bank_mask:0xf bound_ctrl:1
	v_pk_fma_f32 v[0:1], v[16:17], v[98:99], v[92:93] op_sel_hi:[1,0,1]
	v_pk_fma_f32 v[2:3], v[18:19], v[98:99], v[94:95] op_sel_hi:[1,0,1]
	ds_read_b128 v[56:59], v116 offset:26880
	ds_read_b128 v[60:63], v116 offset:27136
	s_waitcnt lgkmcnt(5)
	v_pk_mul_f32 v[86:87], v[2:3], v[34:35]
	v_pk_mul_f32 v[96:97], v[22:23], v[2:3]
	v_pk_fma_f32 v[86:87], v[0:1], v[32:33], v[86:87]
	v_pk_fma_f32 v[96:97], v[20:21], v[0:1], v[96:97]
	v_add_f32_e32 v98, v86, v87
	v_pk_mul_f32 v[88:89], v[28:29], v[64:65] op_sel_hi:[1,0]
	v_pk_mul_f32 v[90:91], v[30:31], v[64:65] op_sel_hi:[1,0]
	v_add_f32_dpp v98, v98, v98 quad_perm:[1,0,3,2] row_mask:0xf bank_mask:0xf bound_ctrl:1
	v_pk_fma_f32 v[92:93], v[0:1], v[24:25], v[88:89]
	v_pk_fma_f32 v[94:95], v[2:3], v[26:27], v[90:91]
	v_add_f32_dpp v98, v98, v98 quad_perm:[2,3,0,1] row_mask:0xf bank_mask:0xf bound_ctrl:1
	v_add_f32_e32 v85, v96, v97
	ds_read_b128 v[8:11], v116 offset:27904
	v_add_f32_dpp v98, v98, v98 row_half_mirror row_mask:0xf bank_mask:0xf bound_ctrl:1
	ds_read2st64_b32 v[66:67], v115 offset0:108 offset1:114
	ds_read_b128 v[12:15], v116 offset:28160
	v_add_f32_dpp v98, v98, v98 row_mirror row_mask:0xf bank_mask:0xf bound_ctrl:1
	v_pk_fma_f32 v[0:1], v[36:37], v[98:99], v[92:93] op_sel_hi:[1,0,1]
	v_pk_fma_f32 v[2:3], v[38:39], v[98:99], v[94:95] op_sel_hi:[1,0,1]
	ds_read_b128 v[4:7], v116 offset:27648
	ds_read_b128 v[16:19], v116 offset:28416
	ds_read_b128 v[20:23], v116 offset:28672
	v_add_f32_dpp v70, v70, v70 row_ror:8 row_mask:0xf bank_mask:0x3 bound_ctrl:1
	v_add_f32_dpp v70, v78, v78 row_ror:8 row_mask:0xf bank_mask:0xc bound_ctrl:1
	v_add_f32_dpp v71, v71, v71 row_ror:8 row_mask:0xf bank_mask:0x3 bound_ctrl:1
	v_add_f32_dpp v71, v79, v79 row_ror:8 row_mask:0xf bank_mask:0xc bound_ctrl:1
	s_waitcnt lgkmcnt(6)
	v_pk_mul_f32 v[86:87], v[2:3], v[54:55]
	v_pk_mul_f32 v[96:97], v[42:43], v[2:3]
	v_pk_fma_f32 v[86:87], v[0:1], v[52:53], v[86:87]
	v_pk_fma_f32 v[96:97], v[40:41], v[0:1], v[96:97]
	v_add_f32_e32 v98, v86, v87
	v_pk_mul_f32 v[88:89], v[48:49], v[64:65] op_sel:[0,1] op_sel_hi:[1,1]
	v_pk_mul_f32 v[90:91], v[50:51], v[64:65] op_sel:[0,1] op_sel_hi:[1,1]
	v_add_f32_dpp v98, v98, v98 quad_perm:[1,0,3,2] row_mask:0xf bank_mask:0xf bound_ctrl:1
	v_pk_fma_f32 v[92:93], v[0:1], v[44:45], v[88:89]
	v_pk_fma_f32 v[94:95], v[2:3], v[46:47], v[90:91]
	v_add_f32_dpp v98, v98, v98 quad_perm:[2,3,0,1] row_mask:0xf bank_mask:0xf bound_ctrl:1
	v_add_f32_e32 v120, v96, v97
	ds_read_b128 v[28:31], v116 offset:29440
	v_add_f32_dpp v98, v98, v98 row_half_mirror row_mask:0xf bank_mask:0xf bound_ctrl:1
	ds_read_b128 v[32:35], v116 offset:29696
	ds_read_b128 v[24:27], v116 offset:29184
	v_add_f32_dpp v98, v98, v98 row_mirror row_mask:0xf bank_mask:0xf bound_ctrl:1
	v_pk_fma_f32 v[0:1], v[56:57], v[98:99], v[92:93] op_sel_hi:[1,0,1]
	v_pk_fma_f32 v[2:3], v[58:59], v[98:99], v[94:95] op_sel_hi:[1,0,1]
	ds_read_b128 v[36:39], v116 offset:29952
	ds_read_b128 v[40:43], v116 offset:30208
	v_add_f32_dpp v72, v72, v72 row_ror:8 row_mask:0xf bank_mask:0x3 bound_ctrl:1
	v_add_f32_dpp v72, v80, v80 row_ror:8 row_mask:0xf bank_mask:0xc bound_ctrl:1
	v_add_f32_dpp v73, v73, v73 row_ror:8 row_mask:0xf bank_mask:0x3 bound_ctrl:1
	v_add_f32_dpp v73, v81, v81 row_ror:8 row_mask:0xf bank_mask:0xc bound_ctrl:1
	s_waitcnt lgkmcnt(5)
	v_pk_mul_f32 v[86:87], v[2:3], v[14:15]
	v_pk_mul_f32 v[96:97], v[62:63], v[2:3]
	v_pk_fma_f32 v[86:87], v[0:1], v[12:13], v[86:87]
	v_pk_fma_f32 v[96:97], v[60:61], v[0:1], v[96:97]
	v_add_f32_e32 v98, v86, v87
	v_pk_mul_f32 v[88:89], v[8:9], v[66:67] op_sel_hi:[1,0]
	v_pk_mul_f32 v[90:91], v[10:11], v[66:67] op_sel_hi:[1,0]
	v_add_f32_dpp v98, v98, v98 quad_perm:[1,0,3,2] row_mask:0xf bank_mask:0xf bound_ctrl:1
	v_pk_fma_f32 v[92:93], v[0:1], v[4:5], v[88:89]
	v_pk_fma_f32 v[94:95], v[2:3], v[6:7], v[90:91]
	v_add_f32_dpp v98, v98, v98 quad_perm:[2,3,0,1] row_mask:0xf bank_mask:0xf bound_ctrl:1
	v_add_f32_e32 v121, v96, v97
	ds_read_b128 v[48:51], v116 offset:30976
	v_add_f32_dpp v98, v98, v98 row_half_mirror row_mask:0xf bank_mask:0xf bound_ctrl:1
	ds_read2st64_b32 v[64:65], v115 offset0:120 offset1:126
	ds_read_b128 v[52:55], v116 offset:31232
	v_add_f32_dpp v98, v98, v98 row_mirror row_mask:0xf bank_mask:0xf bound_ctrl:1
	v_pk_fma_f32 v[0:1], v[16:17], v[98:99], v[92:93] op_sel_hi:[1,0,1]
	v_pk_fma_f32 v[2:3], v[18:19], v[98:99], v[94:95] op_sel_hi:[1,0,1]
	ds_read_b128 v[44:47], v116 offset:30720
	ds_read_b128 v[56:59], v116 offset:31488
	ds_read_b128 v[60:63], v116 offset:31744
	v_add_f32_dpp v74, v74, v74 row_ror:8 row_mask:0xf bank_mask:0x3 bound_ctrl:1
	v_add_f32_dpp v74, v82, v82 row_ror:8 row_mask:0xf bank_mask:0xc bound_ctrl:1
	v_add_f32_dpp v75, v75, v75 row_ror:8 row_mask:0xf bank_mask:0x3 bound_ctrl:1
	v_add_f32_dpp v75, v83, v83 row_ror:8 row_mask:0xf bank_mask:0xc bound_ctrl:1
	s_waitcnt lgkmcnt(6)
	v_pk_mul_f32 v[86:87], v[2:3], v[34:35]
	v_pk_mul_f32 v[96:97], v[22:23], v[2:3]
	v_pk_fma_f32 v[86:87], v[0:1], v[32:33], v[86:87]
	v_pk_fma_f32 v[96:97], v[20:21], v[0:1], v[96:97]
	v_add_f32_e32 v98, v86, v87
	v_pk_mul_f32 v[88:89], v[28:29], v[66:67] op_sel:[0,1] op_sel_hi:[1,1]
	v_pk_mul_f32 v[90:91], v[30:31], v[66:67] op_sel:[0,1] op_sel_hi:[1,1]
	v_add_f32_dpp v98, v98, v98 quad_perm:[1,0,3,2] row_mask:0xf bank_mask:0xf bound_ctrl:1
	v_pk_fma_f32 v[92:93], v[0:1], v[24:25], v[88:89]
	v_pk_fma_f32 v[94:95], v[2:3], v[26:27], v[90:91]
	v_add_f32_dpp v98, v98, v98 quad_perm:[2,3,0,1] row_mask:0xf bank_mask:0xf bound_ctrl:1
	v_add_f32_e32 v122, v96, v97
	ds_read_b128 v[8:11], v116 offset:32512
	v_add_f32_dpp v98, v98, v98 row_half_mirror row_mask:0xf bank_mask:0xf bound_ctrl:1
	ds_read_b128 v[12:15], v116 offset:32768
	ds_read_b128 v[4:7], v116 offset:32256
	v_add_f32_dpp v98, v98, v98 row_mirror row_mask:0xf bank_mask:0xf bound_ctrl:1
	v_pk_fma_f32 v[0:1], v[36:37], v[98:99], v[92:93] op_sel_hi:[1,0,1]
	v_pk_fma_f32 v[2:3], v[38:39], v[98:99], v[94:95] op_sel_hi:[1,0,1]
	ds_read_b128 v[16:19], v116 offset:33024
	ds_read_b128 v[20:23], v116 offset:33280
	v_add_f32_dpp v76, v76, v76 row_ror:8 row_mask:0xf bank_mask:0x3 bound_ctrl:1
	v_add_f32_dpp v76, v84, v84 row_ror:8 row_mask:0xf bank_mask:0xc bound_ctrl:1
	v_add_f32_dpp v77, v77, v77 row_ror:8 row_mask:0xf bank_mask:0x3 bound_ctrl:1
	v_add_f32_dpp v77, v85, v85 row_ror:8 row_mask:0xf bank_mask:0xc bound_ctrl:1
	s_waitcnt lgkmcnt(5)
	v_pk_mul_f32 v[86:87], v[2:3], v[54:55]
	v_pk_mul_f32 v[96:97], v[42:43], v[2:3]
	v_pk_fma_f32 v[86:87], v[0:1], v[52:53], v[86:87]
	v_pk_fma_f32 v[96:97], v[40:41], v[0:1], v[96:97]
	v_add_f32_e32 v98, v86, v87
	v_pk_mul_f32 v[88:89], v[48:49], v[64:65] op_sel_hi:[1,0]
	v_pk_mul_f32 v[90:91], v[50:51], v[64:65] op_sel_hi:[1,0]
	v_add_f32_dpp v98, v98, v98 quad_perm:[1,0,3,2] row_mask:0xf bank_mask:0xf bound_ctrl:1
	v_pk_fma_f32 v[92:93], v[0:1], v[44:45], v[88:89]
	v_pk_fma_f32 v[94:95], v[2:3], v[46:47], v[90:91]
	v_add_f32_dpp v98, v98, v98 quad_perm:[2,3,0,1] row_mask:0xf bank_mask:0xf bound_ctrl:1
	v_add_f32_e32 v123, v96, v97
	ds_read_b128 v[28:31], v116 offset:34048
	v_add_f32_dpp v98, v98, v98 row_half_mirror row_mask:0xf bank_mask:0xf bound_ctrl:1
	ds_read2st64_b32 v[66:67], v115 offset0:132 offset1:138
	ds_read_b128 v[32:35], v116 offset:34304
	v_add_f32_dpp v98, v98, v98 row_mirror row_mask:0xf bank_mask:0xf bound_ctrl:1
	v_pk_fma_f32 v[0:1], v[56:57], v[98:99], v[92:93] op_sel_hi:[1,0,1]
	v_pk_fma_f32 v[2:3], v[58:59], v[98:99], v[94:95] op_sel_hi:[1,0,1]
	ds_read_b128 v[24:27], v116 offset:33792
	ds_read_b128 v[36:39], v116 offset:34560
	ds_read_b128 v[40:43], v116 offset:34816
	v_add_f32_dpp v70, v70, v70 row_shl:4 row_mask:0xf bank_mask:0x5 bound_ctrl:1
	v_add_f32_dpp v70, v74, v74 row_shr:4 row_mask:0xf bank_mask:0xa bound_ctrl:1
	v_add_f32_dpp v71, v71, v71 row_shl:4 row_mask:0xf bank_mask:0x5 bound_ctrl:1
	v_add_f32_dpp v71, v75, v75 row_shr:4 row_mask:0xf bank_mask:0xa bound_ctrl:1
	s_waitcnt lgkmcnt(6)
	v_pk_mul_f32 v[86:87], v[2:3], v[14:15]
	v_pk_mul_f32 v[96:97], v[62:63], v[2:3]
	v_pk_fma_f32 v[86:87], v[0:1], v[12:13], v[86:87]
	v_pk_fma_f32 v[96:97], v[60:61], v[0:1], v[96:97]
	v_add_f32_e32 v98, v86, v87
	v_pk_mul_f32 v[88:89], v[8:9], v[64:65] op_sel:[0,1] op_sel_hi:[1,1]
	v_pk_mul_f32 v[90:91], v[10:11], v[64:65] op_sel:[0,1] op_sel_hi:[1,1]
	v_add_f32_dpp v98, v98, v98 quad_perm:[1,0,3,2] row_mask:0xf bank_mask:0xf bound_ctrl:1
	v_pk_fma_f32 v[92:93], v[0:1], v[4:5], v[88:89]
	v_pk_fma_f32 v[94:95], v[2:3], v[6:7], v[90:91]
	v_add_f32_dpp v98, v98, v98 quad_perm:[2,3,0,1] row_mask:0xf bank_mask:0xf bound_ctrl:1
	v_add_f32_e32 v124, v96, v97
	ds_read_b128 v[48:51], v116 offset:35584
	v_add_f32_dpp v98, v98, v98 row_half_mirror row_mask:0xf bank_mask:0xf bound_ctrl:1
	ds_read_b128 v[52:55], v116 offset:35840
	ds_read_b128 v[44:47], v116 offset:35328
	v_add_f32_dpp v98, v98, v98 row_mirror row_mask:0xf bank_mask:0xf bound_ctrl:1
	v_pk_fma_f32 v[0:1], v[16:17], v[98:99], v[92:93] op_sel_hi:[1,0,1]
	v_pk_fma_f32 v[2:3], v[18:19], v[98:99], v[94:95] op_sel_hi:[1,0,1]
	ds_read_b128 v[56:59], v116 offset:36096
	ds_read_b128 v[60:63], v116 offset:36352
	v_add_f32_dpp v72, v72, v72 row_shl:4 row_mask:0xf bank_mask:0x5 bound_ctrl:1
	v_add_f32_dpp v72, v76, v76 row_shr:4 row_mask:0xf bank_mask:0xa bound_ctrl:1
	v_add_f32_dpp v73, v73, v73 row_shl:4 row_mask:0xf bank_mask:0x5 bound_ctrl:1
	v_add_f32_dpp v73, v77, v77 row_shr:4 row_mask:0xf bank_mask:0xa bound_ctrl:1
	s_waitcnt lgkmcnt(5)
	v_pk_mul_f32 v[86:87], v[2:3], v[34:35]
	v_pk_mul_f32 v[96:97], v[22:23], v[2:3]
	v_pk_fma_f32 v[86:87], v[0:1], v[32:33], v[86:87]
	v_pk_fma_f32 v[96:97], v[20:21], v[0:1], v[96:97]
	v_add_f32_e32 v98, v86, v87
	v_pk_mul_f32 v[88:89], v[28:29], v[66:67] op_sel_hi:[1,0]
	v_pk_mul_f32 v[90:91], v[30:31], v[66:67] op_sel_hi:[1,0]
	v_add_f32_dpp v98, v98, v98 quad_perm:[1,0,3,2] row_mask:0xf bank_mask:0xf bound_ctrl:1
	v_pk_fma_f32 v[92:93], v[0:1], v[24:25], v[88:89]
	v_pk_fma_f32 v[94:95], v[2:3], v[26:27], v[90:91]
	v_add_f32_dpp v98, v98, v98 quad_perm:[2,3,0,1] row_mask:0xf bank_mask:0xf bound_ctrl:1
	v_add_f32_e32 v125, v96, v97
	ds_read_b128 v[8:11], v116 offset:37120
	v_add_f32_dpp v98, v98, v98 row_half_mirror row_mask:0xf bank_mask:0xf bound_ctrl:1
	ds_read2st64_b32 v[64:65], v115 offset0:144 offset1:150
	ds_read_b128 v[12:15], v116 offset:37376
	v_add_f32_dpp v98, v98, v98 row_mirror row_mask:0xf bank_mask:0xf bound_ctrl:1
	v_pk_fma_f32 v[0:1], v[36:37], v[98:99], v[92:93] op_sel_hi:[1,0,1]
	v_pk_fma_f32 v[2:3], v[38:39], v[98:99], v[94:95] op_sel_hi:[1,0,1]
	ds_read_b128 v[4:7], v116 offset:36864
	ds_read_b128 v[16:19], v116 offset:37632
	ds_read_b128 v[20:23], v116 offset:37888
	v_add_f32_dpp v70, v70, v70 quad_perm:[1,0,3,2] row_mask:0xf bank_mask:0xf bound_ctrl:1
	v_add_f32_dpp v71, v71, v71 quad_perm:[1,0,3,2] row_mask:0xf bank_mask:0xf bound_ctrl:1
	v_add_f32_dpp v72, v72, v72 quad_perm:[1,0,3,2] row_mask:0xf bank_mask:0xf bound_ctrl:1
	v_add_f32_dpp v73, v73, v73 quad_perm:[1,0,3,2] row_mask:0xf bank_mask:0xf bound_ctrl:1
	s_waitcnt lgkmcnt(6)
	v_pk_mul_f32 v[86:87], v[2:3], v[54:55]
	v_pk_mul_f32 v[96:97], v[42:43], v[2:3]
	v_pk_fma_f32 v[86:87], v[0:1], v[52:53], v[86:87]
	v_pk_fma_f32 v[96:97], v[40:41], v[0:1], v[96:97]
	v_add_f32_e32 v98, v86, v87
	v_pk_mul_f32 v[88:89], v[48:49], v[66:67] op_sel:[0,1] op_sel_hi:[1,1]
	v_pk_mul_f32 v[90:91], v[50:51], v[66:67] op_sel:[0,1] op_sel_hi:[1,1]
	v_add_f32_dpp v98, v98, v98 quad_perm:[1,0,3,2] row_mask:0xf bank_mask:0xf bound_ctrl:1
	v_pk_fma_f32 v[92:93], v[0:1], v[44:45], v[88:89]
	v_pk_fma_f32 v[94:95], v[2:3], v[46:47], v[90:91]
	v_add_f32_dpp v98, v98, v98 quad_perm:[2,3,0,1] row_mask:0xf bank_mask:0xf bound_ctrl:1
	v_add_f32_e32 v126, v96, v97
	ds_read_b128 v[28:31], v116 offset:38656
	v_add_f32_dpp v98, v98, v98 row_half_mirror row_mask:0xf bank_mask:0xf bound_ctrl:1
	ds_read_b128 v[32:35], v116 offset:38912
	ds_read_b128 v[24:27], v116 offset:38400
	v_add_f32_dpp v98, v98, v98 row_mirror row_mask:0xf bank_mask:0xf bound_ctrl:1
	v_pk_fma_f32 v[0:1], v[56:57], v[98:99], v[92:93] op_sel_hi:[1,0,1]
	v_pk_fma_f32 v[2:3], v[58:59], v[98:99], v[94:95] op_sel_hi:[1,0,1]
	ds_read_b128 v[36:39], v116 offset:39168
	ds_read_b128 v[40:43], v116 offset:39424
	v_add_f32_dpp v70, v70, v70 quad_perm:[2,3,0,1] row_mask:0xf bank_mask:0xf bound_ctrl:1
	v_add_f32_dpp v71, v71, v71 quad_perm:[2,3,0,1] row_mask:0xf bank_mask:0xf bound_ctrl:1
	v_add_f32_dpp v72, v72, v72 quad_perm:[2,3,0,1] row_mask:0xf bank_mask:0xf bound_ctrl:1
	v_add_f32_dpp v73, v73, v73 quad_perm:[2,3,0,1] row_mask:0xf bank_mask:0xf bound_ctrl:1
	s_waitcnt lgkmcnt(5)
	v_pk_mul_f32 v[86:87], v[2:3], v[14:15]
	v_pk_mul_f32 v[96:97], v[62:63], v[2:3]
	v_pk_fma_f32 v[86:87], v[0:1], v[12:13], v[86:87]
	v_pk_fma_f32 v[96:97], v[60:61], v[0:1], v[96:97]
	v_add_f32_e32 v98, v86, v87
	v_pk_mul_f32 v[88:89], v[8:9], v[64:65] op_sel_hi:[1,0]
	v_pk_mul_f32 v[90:91], v[10:11], v[64:65] op_sel_hi:[1,0]
	v_add_f32_dpp v98, v98, v98 quad_perm:[1,0,3,2] row_mask:0xf bank_mask:0xf bound_ctrl:1
	v_pk_fma_f32 v[92:93], v[0:1], v[4:5], v[88:89]
	v_pk_fma_f32 v[94:95], v[2:3], v[6:7], v[90:91]
	v_add_f32_dpp v98, v98, v98 quad_perm:[2,3,0,1] row_mask:0xf bank_mask:0xf bound_ctrl:1
	v_add_f32_e32 v127, v96, v97
	ds_read_b128 v[48:51], v116 offset:40192
	v_add_f32_dpp v98, v98, v98 row_half_mirror row_mask:0xf bank_mask:0xf bound_ctrl:1
	ds_read2st64_b32 v[66:67], v115 offset0:156 offset1:162
	ds_read_b128 v[52:55], v116 offset:40448
	v_add_f32_dpp v98, v98, v98 row_mirror row_mask:0xf bank_mask:0xf bound_ctrl:1
	v_pk_fma_f32 v[0:1], v[16:17], v[98:99], v[92:93] op_sel_hi:[1,0,1]
	v_pk_fma_f32 v[2:3], v[18:19], v[98:99], v[94:95] op_sel_hi:[1,0,1]
	ds_read_b128 v[44:47], v116 offset:39936
	ds_read_b128 v[56:59], v116 offset:40704
	ds_read_b128 v[60:63], v116 offset:40960
	v_cndmask_b32_e64 v109, v70, v71, s[4:5]
	v_cndmask_b32_e64 v109, v109, v72, s[10:11]
	v_cndmask_b32_e64 v109, v109, v73, s[12:13]
	v_bfe_u32 v108, v109, 16, 1
	s_waitcnt lgkmcnt(6)
	v_pk_mul_f32 v[86:87], v[2:3], v[34:35]
	v_pk_mul_f32 v[96:97], v[22:23], v[2:3]
	v_pk_fma_f32 v[86:87], v[0:1], v[32:33], v[86:87]
	v_pk_fma_f32 v[96:97], v[20:21], v[0:1], v[96:97]
	v_add_f32_e32 v98, v86, v87
	v_pk_mul_f32 v[88:89], v[28:29], v[64:65] op_sel:[0,1] op_sel_hi:[1,1]
	v_pk_mul_f32 v[90:91], v[30:31], v[64:65] op_sel:[0,1] op_sel_hi:[1,1]
	v_add_f32_dpp v98, v98, v98 quad_perm:[1,0,3,2] row_mask:0xf bank_mask:0xf bound_ctrl:1
	v_pk_fma_f32 v[92:93], v[0:1], v[24:25], v[88:89]
	v_pk_fma_f32 v[94:95], v[2:3], v[26:27], v[90:91]
	v_add_f32_dpp v98, v98, v98 quad_perm:[2,3,0,1] row_mask:0xf bank_mask:0xf bound_ctrl:1
	v_add_f32_e32 v128, v96, v97
	ds_read_b128 v[8:11], v116 offset:41728
	v_add_f32_dpp v98, v98, v98 row_half_mirror row_mask:0xf bank_mask:0xf bound_ctrl:1
	ds_read_b128 v[12:15], v116 offset:41984
	ds_read_b128 v[4:7], v116 offset:41472
	v_add_f32_dpp v98, v98, v98 row_mirror row_mask:0xf bank_mask:0xf bound_ctrl:1
	v_pk_fma_f32 v[0:1], v[36:37], v[98:99], v[92:93] op_sel_hi:[1,0,1]
	v_pk_fma_f32 v[2:3], v[38:39], v[98:99], v[94:95] op_sel_hi:[1,0,1]
	ds_read_b128 v[16:19], v116 offset:42240
	ds_read_b128 v[20:23], v116 offset:42496
	v_mov_b32_e32 v102, v114
	v_add3_u32 v108, v109, v108, s7
	v_lshl_add_u64 v[106:107], v[102:103], 1, v[104:105]
	global_store_short_d16_hi v[106:107], v108, off
	s_waitcnt lgkmcnt(5)
	v_pk_mul_f32 v[86:87], v[2:3], v[54:55]
	v_pk_mul_f32 v[96:97], v[42:43], v[2:3]
	v_pk_fma_f32 v[86:87], v[0:1], v[52:53], v[86:87]
	v_pk_fma_f32 v[96:97], v[40:41], v[0:1], v[96:97]
	v_add_f32_e32 v98, v86, v87
	v_pk_mul_f32 v[88:89], v[48:49], v[66:67] op_sel_hi:[1,0]
	v_pk_mul_f32 v[90:91], v[50:51], v[66:67] op_sel_hi:[1,0]
	v_add_f32_dpp v98, v98, v98 quad_perm:[1,0,3,2] row_mask:0xf bank_mask:0xf bound_ctrl:1
	v_pk_fma_f32 v[92:93], v[0:1], v[44:45], v[88:89]
	v_pk_fma_f32 v[94:95], v[2:3], v[46:47], v[90:91]
	v_add_f32_dpp v98, v98, v98 quad_perm:[2,3,0,1] row_mask:0xf bank_mask:0xf bound_ctrl:1
	v_add_f32_e32 v129, v96, v97
	ds_read_b128 v[28:31], v116 offset:43264
	v_add_f32_dpp v98, v98, v98 row_half_mirror row_mask:0xf bank_mask:0xf bound_ctrl:1
	ds_read2st64_b32 v[64:65], v115 offset0:168 offset1:174
	ds_read_b128 v[32:35], v116 offset:43520
	v_add_f32_dpp v98, v98, v98 row_mirror row_mask:0xf bank_mask:0xf bound_ctrl:1
	v_pk_fma_f32 v[0:1], v[56:57], v[98:99], v[92:93] op_sel_hi:[1,0,1]
	v_pk_fma_f32 v[2:3], v[58:59], v[98:99], v[94:95] op_sel_hi:[1,0,1]
	ds_read_b128 v[24:27], v116 offset:43008
	ds_read_b128 v[36:39], v116 offset:43776
	ds_read_b128 v[40:43], v116 offset:44032
	s_waitcnt lgkmcnt(6)
	v_pk_mul_f32 v[86:87], v[2:3], v[14:15]
	v_pk_mul_f32 v[96:97], v[62:63], v[2:3]
	v_pk_fma_f32 v[86:87], v[0:1], v[12:13], v[86:87]
	v_pk_fma_f32 v[96:97], v[60:61], v[0:1], v[96:97]
	v_add_f32_e32 v98, v86, v87
	v_pk_mul_f32 v[88:89], v[8:9], v[66:67] op_sel:[0,1] op_sel_hi:[1,1]
	v_pk_mul_f32 v[90:91], v[10:11], v[66:67] op_sel:[0,1] op_sel_hi:[1,1]
	v_add_f32_dpp v98, v98, v98 quad_perm:[1,0,3,2] row_mask:0xf bank_mask:0xf bound_ctrl:1
	v_pk_fma_f32 v[92:93], v[0:1], v[4:5], v[88:89]
	v_pk_fma_f32 v[94:95], v[2:3], v[6:7], v[90:91]
	v_add_f32_dpp v98, v98, v98 quad_perm:[2,3,0,1] row_mask:0xf bank_mask:0xf bound_ctrl:1
	v_add_f32_e32 v130, v96, v97
	ds_read_b128 v[48:51], v116 offset:44800
	v_add_f32_dpp v98, v98, v98 row_half_mirror row_mask:0xf bank_mask:0xf bound_ctrl:1
	ds_read_b128 v[52:55], v116 offset:45056
	ds_read_b128 v[44:47], v116 offset:44544
	v_add_f32_dpp v98, v98, v98 row_mirror row_mask:0xf bank_mask:0xf bound_ctrl:1
	v_pk_fma_f32 v[0:1], v[16:17], v[98:99], v[92:93] op_sel_hi:[1,0,1]
	v_pk_fma_f32 v[2:3], v[18:19], v[98:99], v[94:95] op_sel_hi:[1,0,1]
	ds_read_b128 v[56:59], v116 offset:45312
	ds_read_b128 v[60:63], v116 offset:45568
	s_waitcnt lgkmcnt(5)
	v_pk_mul_f32 v[86:87], v[2:3], v[34:35]
	v_pk_mul_f32 v[96:97], v[22:23], v[2:3]
	v_pk_fma_f32 v[86:87], v[0:1], v[32:33], v[86:87]
	v_pk_fma_f32 v[96:97], v[20:21], v[0:1], v[96:97]
	v_add_f32_e32 v98, v86, v87
	v_pk_mul_f32 v[88:89], v[28:29], v[64:65] op_sel_hi:[1,0]
	v_pk_mul_f32 v[90:91], v[30:31], v[64:65] op_sel_hi:[1,0]
	v_add_f32_dpp v98, v98, v98 quad_perm:[1,0,3,2] row_mask:0xf bank_mask:0xf bound_ctrl:1
	v_pk_fma_f32 v[92:93], v[0:1], v[24:25], v[88:89]
	v_pk_fma_f32 v[94:95], v[2:3], v[26:27], v[90:91]
	v_add_f32_dpp v98, v98, v98 quad_perm:[2,3,0,1] row_mask:0xf bank_mask:0xf bound_ctrl:1
	v_add_f32_e32 v131, v96, v97
	ds_read_b128 v[8:11], v116 offset:46336
	v_add_f32_dpp v98, v98, v98 row_half_mirror row_mask:0xf bank_mask:0xf bound_ctrl:1
	ds_read2st64_b32 v[66:67], v115 offset0:180 offset1:186
	ds_read_b128 v[12:15], v116 offset:46592
	v_add_f32_dpp v98, v98, v98 row_mirror row_mask:0xf bank_mask:0xf bound_ctrl:1
	v_pk_fma_f32 v[0:1], v[36:37], v[98:99], v[92:93] op_sel_hi:[1,0,1]
	v_pk_fma_f32 v[2:3], v[38:39], v[98:99], v[94:95] op_sel_hi:[1,0,1]
	ds_read_b128 v[4:7], v116 offset:46080
	ds_read_b128 v[16:19], v116 offset:46848
	ds_read_b128 v[20:23], v116 offset:47104
	s_waitcnt lgkmcnt(6)
	v_pk_mul_f32 v[86:87], v[2:3], v[54:55]
	v_pk_mul_f32 v[96:97], v[42:43], v[2:3]
	v_pk_fma_f32 v[86:87], v[0:1], v[52:53], v[86:87]
	v_pk_fma_f32 v[96:97], v[40:41], v[0:1], v[96:97]
	v_add_f32_e32 v98, v86, v87
	v_pk_mul_f32 v[88:89], v[48:49], v[64:65] op_sel:[0,1] op_sel_hi:[1,1]
	v_pk_mul_f32 v[90:91], v[50:51], v[64:65] op_sel:[0,1] op_sel_hi:[1,1]
	v_add_f32_dpp v98, v98, v98 quad_perm:[1,0,3,2] row_mask:0xf bank_mask:0xf bound_ctrl:1
	v_pk_fma_f32 v[92:93], v[0:1], v[44:45], v[88:89]
	v_pk_fma_f32 v[94:95], v[2:3], v[46:47], v[90:91]
	v_add_f32_dpp v98, v98, v98 quad_perm:[2,3,0,1] row_mask:0xf bank_mask:0xf bound_ctrl:1
	v_add_f32_e32 v132, v96, v97
	ds_read_b128 v[28:31], v116 offset:47872
	v_add_f32_dpp v98, v98, v98 row_half_mirror row_mask:0xf bank_mask:0xf bound_ctrl:1
	ds_read_b128 v[32:35], v116 offset:48128
	ds_read_b128 v[24:27], v116 offset:47616
	v_add_f32_dpp v98, v98, v98 row_mirror row_mask:0xf bank_mask:0xf bound_ctrl:1
	v_pk_fma_f32 v[0:1], v[56:57], v[98:99], v[92:93] op_sel_hi:[1,0,1]
	v_pk_fma_f32 v[2:3], v[58:59], v[98:99], v[94:95] op_sel_hi:[1,0,1]
	ds_read_b128 v[36:39], v116 offset:48384
	ds_read_b128 v[40:43], v116 offset:48640
	s_waitcnt lgkmcnt(5)
	v_pk_mul_f32 v[86:87], v[2:3], v[14:15]
	v_pk_mul_f32 v[96:97], v[62:63], v[2:3]
	v_pk_fma_f32 v[86:87], v[0:1], v[12:13], v[86:87]
	v_pk_fma_f32 v[96:97], v[60:61], v[0:1], v[96:97]
	v_add_f32_e32 v98, v86, v87
	v_pk_mul_f32 v[88:89], v[8:9], v[66:67] op_sel_hi:[1,0]
	v_pk_mul_f32 v[90:91], v[10:11], v[66:67] op_sel_hi:[1,0]
	v_add_f32_dpp v98, v98, v98 quad_perm:[1,0,3,2] row_mask:0xf bank_mask:0xf bound_ctrl:1
	v_pk_fma_f32 v[92:93], v[0:1], v[4:5], v[88:89]
	v_pk_fma_f32 v[94:95], v[2:3], v[6:7], v[90:91]
	v_add_f32_dpp v98, v98, v98 quad_perm:[2,3,0,1] row_mask:0xf bank_mask:0xf bound_ctrl:1
	v_add_f32_e32 v133, v96, v97
	s_nop 0
	v_add_f32_dpp v98, v98, v98 row_half_mirror row_mask:0xf bank_mask:0xf bound_ctrl:1
	s_nop 0
	s_nop 0
	v_add_f32_dpp v98, v98, v98 row_mirror row_mask:0xf bank_mask:0xf bound_ctrl:1
	v_pk_fma_f32 v[0:1], v[16:17], v[98:99], v[92:93] op_sel_hi:[1,0,1]
	v_pk_fma_f32 v[2:3], v[18:19], v[98:99], v[94:95] op_sel_hi:[1,0,1]
	s_waitcnt lgkmcnt(0)
	v_pk_mul_f32 v[86:87], v[2:3], v[34:35]
	v_pk_mul_f32 v[96:97], v[22:23], v[2:3]
	v_pk_fma_f32 v[86:87], v[0:1], v[32:33], v[86:87]
	v_pk_fma_f32 v[96:97], v[20:21], v[0:1], v[96:97]
	v_add_f32_e32 v98, v86, v87
	v_pk_mul_f32 v[88:89], v[28:29], v[66:67] op_sel:[0,1] op_sel_hi:[1,1]
	v_pk_mul_f32 v[90:91], v[30:31], v[66:67] op_sel:[0,1] op_sel_hi:[1,1]
	v_add_f32_dpp v98, v98, v98 quad_perm:[1,0,3,2] row_mask:0xf bank_mask:0xf bound_ctrl:1
	v_pk_fma_f32 v[92:93], v[0:1], v[24:25], v[88:89]
	v_pk_fma_f32 v[94:95], v[2:3], v[26:27], v[90:91]
	v_add_f32_dpp v98, v98, v98 quad_perm:[2,3,0,1] row_mask:0xf bank_mask:0xf bound_ctrl:1
	v_add_f32_e32 v134, v96, v97
	s_nop 0
	v_add_f32_dpp v98, v98, v98 row_half_mirror row_mask:0xf bank_mask:0xf bound_ctrl:1
	s_nop 0
	s_nop 0
	v_add_f32_dpp v98, v98, v98 row_mirror row_mask:0xf bank_mask:0xf bound_ctrl:1
	v_pk_fma_f32 v[0:1], v[36:37], v[98:99], v[92:93] op_sel_hi:[1,0,1]
	v_pk_fma_f32 v[2:3], v[38:39], v[98:99], v[94:95] op_sel_hi:[1,0,1]
	v_pk_mul_f32 v[96:97], v[42:43], v[2:3]
	s_nop 0
	v_pk_fma_f32 v[96:97], v[40:41], v[0:1], v[96:97]
	v_add_f32_e32 v135, v96, v97
	s_nop 1
	v_add_f32_dpp v120, v120, v120 row_ror:8 row_mask:0xf bank_mask:0x3 bound_ctrl:1
	v_add_f32_dpp v120, v128, v128 row_ror:8 row_mask:0xf bank_mask:0xc bound_ctrl:1
	v_add_f32_dpp v121, v121, v121 row_ror:8 row_mask:0xf bank_mask:0x3 bound_ctrl:1
	v_add_f32_dpp v121, v129, v129 row_ror:8 row_mask:0xf bank_mask:0xc bound_ctrl:1
	v_add_f32_dpp v122, v122, v122 row_ror:8 row_mask:0xf bank_mask:0x3 bound_ctrl:1
	v_add_f32_dpp v122, v130, v130 row_ror:8 row_mask:0xf bank_mask:0xc bound_ctrl:1
	v_add_f32_dpp v123, v123, v123 row_ror:8 row_mask:0xf bank_mask:0x3 bound_ctrl:1
	v_add_f32_dpp v123, v131, v131 row_ror:8 row_mask:0xf bank_mask:0xc bound_ctrl:1
	v_add_f32_dpp v124, v124, v124 row_ror:8 row_mask:0xf bank_mask:0x3 bound_ctrl:1
	v_add_f32_dpp v124, v132, v132 row_ror:8 row_mask:0xf bank_mask:0xc bound_ctrl:1
	v_add_f32_dpp v125, v125, v125 row_ror:8 row_mask:0xf bank_mask:0x3 bound_ctrl:1
	v_add_f32_dpp v125, v133, v133 row_ror:8 row_mask:0xf bank_mask:0xc bound_ctrl:1
	v_add_f32_dpp v126, v126, v126 row_ror:8 row_mask:0xf bank_mask:0x3 bound_ctrl:1
	v_add_f32_dpp v126, v134, v134 row_ror:8 row_mask:0xf bank_mask:0xc bound_ctrl:1
	v_add_f32_dpp v127, v127, v127 row_ror:8 row_mask:0xf bank_mask:0x3 bound_ctrl:1
	v_add_f32_dpp v127, v135, v135 row_ror:8 row_mask:0xf bank_mask:0xc bound_ctrl:1
	v_add_f32_dpp v120, v120, v120 row_shl:4 row_mask:0xf bank_mask:0x5 bound_ctrl:1
	v_add_f32_dpp v120, v124, v124 row_shr:4 row_mask:0xf bank_mask:0xa bound_ctrl:1
	v_add_f32_dpp v121, v121, v121 row_shl:4 row_mask:0xf bank_mask:0x5 bound_ctrl:1
	v_add_f32_dpp v121, v125, v125 row_shr:4 row_mask:0xf bank_mask:0xa bound_ctrl:1
	v_add_f32_dpp v122, v122, v122 row_shl:4 row_mask:0xf bank_mask:0x5 bound_ctrl:1
	v_add_f32_dpp v122, v126, v126 row_shr:4 row_mask:0xf bank_mask:0xa bound_ctrl:1
	v_add_f32_dpp v123, v123, v123 row_shl:4 row_mask:0xf bank_mask:0x5 bound_ctrl:1
	v_add_f32_dpp v123, v127, v127 row_shr:4 row_mask:0xf bank_mask:0xa bound_ctrl:1
	v_add_f32_dpp v120, v120, v120 quad_perm:[1,0,3,2] row_mask:0xf bank_mask:0xf bound_ctrl:1
	v_add_f32_dpp v121, v121, v121 quad_perm:[1,0,3,2] row_mask:0xf bank_mask:0xf bound_ctrl:1
	v_add_f32_dpp v122, v122, v122 quad_perm:[1,0,3,2] row_mask:0xf bank_mask:0xf bound_ctrl:1
	v_add_f32_dpp v123, v123, v123 quad_perm:[1,0,3,2] row_mask:0xf bank_mask:0xf bound_ctrl:1
	v_add_f32_dpp v120, v120, v120 quad_perm:[2,3,0,1] row_mask:0xf bank_mask:0xf bound_ctrl:1
	v_add_f32_dpp v121, v121, v121 quad_perm:[2,3,0,1] row_mask:0xf bank_mask:0xf bound_ctrl:1
	v_add_f32_dpp v122, v122, v122 quad_perm:[2,3,0,1] row_mask:0xf bank_mask:0xf bound_ctrl:1
	v_add_f32_dpp v123, v123, v123 quad_perm:[2,3,0,1] row_mask:0xf bank_mask:0xf bound_ctrl:1
	v_cndmask_b32_e64 v109, v120, v121, s[4:5]
	v_cndmask_b32_e64 v109, v109, v122, s[10:11]
	v_cndmask_b32_e64 v109, v109, v123, s[12:13]
	v_bfe_u32 v108, v109, 16, 1
	v_or_b32_e32 v102, 0x8000, v114
	v_add3_u32 v108, v109, v108, s7
	v_lshl_add_u64 v[106:107], v[102:103], 1, v[104:105]
	global_store_short_d16_hi v[106:107], v108, off
	s_add_i32 s6, s6, 1
	s_cmpk_eq_i32 s6, 0x80
	s_barrier
	s_cbranch_scc0 .LBB0_996
	s_lshl_b32 s0, s24, 16
	s_lshl_b32 s1, s25, 12
	s_or_b32 s0, s1, s0
	s_mov_b32 s1, 0
	s_lshl_b64 s[0:1], s[0:1], 2
	v_lshlrev_b64 v[4:5], 8, v[100:101]
	v_or_b32_e32 v5, s1, v5
	v_or_b32_e32 v4, s0, v4
	v_lshl_add_u64 v[4:5], s[92:93], 0, v[4:5]
	v_lshlrev_b32_e32 v6, 4, v110
	v_mov_b32_e32 v7, 0
	v_lshl_add_u64 v[4:5], v[4:5], 0, v[6:7]
	v_add_co_u32_e32 v4, vcc, 0x8180000, v4
	s_nop 1
	v_addc_co_u32_e32 v5, vcc, 0, v5, vcc
	global_store_dwordx4 v[4:5], v[0:3], off
